# rs_precompute: closed-form tile index, the two row-sum sets a workgroup needs loaded once (instead of one set per unit), on top of the 4/4/4/4 DMA staging
# speedup vs baseline: 1.0162x; 1.0032x over previous
.LBB0_692:
	s_or_b64 exec, exec, s[0:1]
	s_waitcnt lgkmcnt(0)
	v_mov_b32_e32 v0, v181
	s_barrier
	s_cmp_eq_u32 s66, 0x100
	s_cbranch_scc0 .Lrs_orig_g0
	v_lshrrev_b32_e32 v4, 8, v181
	v_and_b32_e32 v5, 0xff, v181
	v_mov_b32_e32 v9, 0x358637bd
	v_readfirstlane_b32 s4, v4
	v_lshlrev_b32_e32 v6, 6, v5
	v_lshlrev_b32_e32 v7, 2, v5
	s_nop 3
	s_and_b32 s5, s2, 7
	s_lshr_b32 s9, s2, 3
	s_lshl_b32 s5, s5, 4
	s_and_b32 s10, s9, 7
	s_add_i32 s5, s5, s10
	s_lshl_b32 s10, s4, 10
	s_add_i32 s10, s10, 0x20000
	v_add_u32_e32 v7, s10, v7
	s_lshl_b32 s11, s5, 14
	s_add_u32 s12, s68, s11
	s_addc_u32 s13, s69, 0
	s_add_u32 s98, s12, 0x20000
	s_addc_u32 s99, s13, 0
	global_load_dwordx4 v[16:19], v6, s[12:13] offset:0
	global_load_dwordx4 v[20:23], v6, s[12:13] offset:16
	global_load_dwordx4 v[24:27], v6, s[12:13] offset:32
	global_load_dwordx4 v[28:31], v6, s[12:13] offset:48
	global_load_dwordx4 v[32:35], v6, s[98:99] offset:0
	global_load_dwordx4 v[36:39], v6, s[98:99] offset:16
	global_load_dwordx4 v[40:43], v6, s[98:99] offset:32
	global_load_dwordx4 v[44:47], v6, s[98:99] offset:48
	s_waitcnt vmcnt(4)
	v_add_f32_e32 v12, v16, v17
	v_add_f32_e32 v48, v18, v19
	v_add_f32_e32 v12, v12, v48
	v_add_f32_e32 v13, v20, v21
	v_add_f32_e32 v48, v22, v23
	v_add_f32_e32 v13, v13, v48
	v_add_f32_e32 v14, v24, v25
	v_add_f32_e32 v48, v26, v27
	v_add_f32_e32 v14, v14, v48
	v_add_f32_e32 v15, v28, v29
	v_add_f32_e32 v48, v30, v31
	v_add_f32_e32 v15, v15, v48
	v_add_f32_e32 v12, v12, v13
	v_add_f32_e32 v12, v12, v14
	v_add_f32_e32 v12, v12, v15
	v_fmamk_f32 v12, v12, 0x3a800000, v9
	v_rsq_f32_e32 v10, v12
	s_waitcnt vmcnt(0)
	v_add_f32_e32 v12, v32, v33
	v_add_f32_e32 v48, v34, v35
	v_add_f32_e32 v12, v12, v48
	v_add_f32_e32 v13, v36, v37
	v_add_f32_e32 v48, v38, v39
	v_add_f32_e32 v13, v13, v48
	v_add_f32_e32 v14, v40, v41
	v_add_f32_e32 v48, v42, v43
	v_add_f32_e32 v14, v14, v48
	v_add_f32_e32 v15, v44, v45
	v_add_f32_e32 v48, v46, v47
	v_add_f32_e32 v15, v15, v48
	v_add_f32_e32 v12, v12, v13
	v_add_f32_e32 v12, v12, v14
	v_add_f32_e32 v12, v12, v15
	v_fmamk_f32 v12, v12, 0x3a800000, v9
	v_rsq_f32_e32 v11, v12
	s_lshl_b32 s11, s4, 5
	s_add_i32 s11, s11, s9
	s_add_i32 s10, s11, 0
	s_cmp_ge_u32 s10, 176
	s_cselect_b64 vcc, -1, 0
	v_cndmask_b32_e32 v12, v10, v11, vcc
	ds_write_b32 v7, v12 offset:0
	s_add_i32 s10, s11, 64
	s_cmp_ge_u32 s10, 176
	s_cselect_b64 vcc, -1, 0
	v_cndmask_b32_e32 v12, v10, v11, vcc
	ds_write_b32 v7, v12 offset:2048
	s_add_i32 s10, s11, 128
	s_cmp_ge_u32 s10, 176
	s_cselect_b64 vcc, -1, 0
	v_cndmask_b32_e32 v12, v10, v11, vcc
	ds_write_b32 v7, v12 offset:4096
	s_add_i32 s10, s11, 192
	s_cmp_ge_u32 s10, 176
	s_cselect_b64 vcc, -1, 0
	v_cndmask_b32_e32 v12, v10, v11, vcc
	ds_write_b32 v7, v12 offset:6144
	s_add_i32 s10, s11, 256
	s_cmp_ge_u32 s10, 176
	s_cselect_b64 vcc, -1, 0
	v_cndmask_b32_e32 v12, v10, v11, vcc
	ds_write_b32 v7, v12 offset:8192
	s_cmp_eq_u32 s4, 0
	s_cbranch_scc0 .Lrs_join_g0
	s_add_i32 s10, s11, 320
	s_cmp_ge_u32 s10, 176
	s_cselect_b64 vcc, -1, 0
	v_cndmask_b32_e32 v12, v10, v11, vcc
	ds_write_b32 v7, v12 offset:10240
	s_branch .Lrs_join_g0
.Lrs_orig_g0:
	s_mov_b64 s[4:5], 0xb00
	v_and_b32_e32 v2, 0xff, v0
	v_ashrrev_i32_e32 v4, 8, v0
	v_lshlrev_b32_e32 v0, 2, v2
	v_lshl_or_b32 v0, v4, 10, v0
	v_add_u32_e32 v0, 0, v0
	v_add_u32_e32 v3, 0x20000, v0
	v_mov_b64_e32 v[0:1], s[2:3]
	v_mad_i64_i32 v[0:1], s[0:1], s72, v4, v[0:1]
	s_mov_b64 s[0:1], 0
	s_mov_b32 s10, 0x2e8ba2e9
	s_movk_i32 s11, 0xb0
	v_mov_b32_e32 v4, 0x358637bd
	v_mov_b32_e32 v5, 0x160
	v_mov_b32_e32 v6, 0x161
	s_branch .LBB0_694

.Lrs_join_g0:
	s_cmpk_lt_i32 s2, 0xb00
	s_cselect_b64 s[0:1], -1, 0
	v_mov_b32_e32 v9, v181
	v_writelane_b32 v246, s0, 58
	s_waitcnt lgkmcnt(0)
	s_barrier
	v_writelane_b32 v246, s1, 59
	s_cmpk_gt_i32 s2, 0xaff
	v_readfirstlane_b32 s1, v9
	s_cbranch_scc1 .LBB0_712
	v_lshlrev_b32_e32 v0, 4, v9
	v_add_u32_e32 v1, 0x2000, v0
	v_ashrrev_i32_e32 v2, 31, v1
	v_lshrrev_b32_e32 v2, 22, v2
	v_add_u32_e32 v2, v1, v2
	v_ashrrev_i32_e32 v8, 10, v2
	v_mul_i32_i24_e32 v2, 0x400, v8
	v_sub_u32_e32 v1, v1, v2
	v_lshrrev_b32_e32 v2, 4, v1
	v_bitop3_b32 v1, v2, v1, 32 bitop3:0x6c
	v_ashrrev_i32_e32 v2, 31, v1
	v_lshrrev_b32_e32 v2, 26, v2
	v_add_u32_e32 v2, v1, v2
	v_lshlrev_b32_e32 v3, 3, v8
	v_ashrrev_i32_e32 v10, 6, v2
	v_and_b32_e32 v3, -16, v3
	v_add_u32_e32 v3, v10, v3
	v_and_b32_e32 v4, 3, v10
	s_mov_b32 s0, 0x1fffe0
	v_lshrrev_b32_e32 v5, 2, v3
	v_lshlrev_b32_e32 v6, 1, v3
	v_and_b32_e32 v2, 0xc0, v2
	v_and_or_b32 v4, v3, s0, v4
	v_and_b32_e32 v5, 4, v5
	v_and_b32_e32 v6, 24, v6
	v_sub_u32_e32 v1, v1, v2
	v_mov_b32_e32 v2, 1
	v_or3_b32 v4, v4, v5, v6
	v_lshlrev_b32_e32 v5, 5, v8
	v_ashrrev_i16_sdwa v1, v2, sext(v1) dst_sel:DWORD dst_unused:UNUSED_PAD src0_sel:DWORD src1_sel:BYTE_0
	v_and_b32_e32 v5, 32, v5
	v_bfe_i32 v11, v1, 0, 16
	v_add_lshl_u32 v1, v5, v11, 1
	v_lshl_add_u32 v128, v4, 11, v1
	v_lshl_add_u32 v130, v3, 11, v1
	v_bfe_i32 v1, v9, 27, 1
	v_lshrrev_b32_e32 v1, 22, v1
	v_add_u32_e32 v1, v0, v1
	v_and_b32_e32 v1, 0xfffffc00, v1
	v_sub_u32_e32 v0, v0, v1
	v_lshrrev_b32_e32 v1, 4, v0
	v_ashrrev_i32_e32 v3, 31, v9
	v_bitop3_b32 v0, v1, v0, 32 bitop3:0x6c
	v_lshrrev_b32_e32 v3, 26, v3
	v_ashrrev_i32_e32 v1, 31, v0
	v_add_u32_e32 v3, v9, v3
	v_lshrrev_b32_e32 v1, 26, v1
	v_ashrrev_i32_e32 v13, 6, v3
	v_add_u32_e32 v1, v0, v1
	v_lshlrev_b32_e32 v3, 3, v13
	v_ashrrev_i32_e32 v12, 6, v1
	v_and_b32_e32 v3, -16, v3
	s_add_u32 s26, s64, 0x980000
	v_add_u32_e32 v3, v12, v3
	v_and_b32_e32 v4, 3, v12
	s_addc_u32 s27, s65, 0
	v_and_or_b32 v4, v3, s0, v4
	s_lshr_b32 s0, s3, 29
	s_add_i32 s0, s2, s0
	s_ashr_i32 s6, s1, 6
	s_ashr_i32 s4, s0, 3
	s_and_b32 s0, s0, -8
	s_ashr_i32 s8, s1, 8
	s_lshl_b32 s28, s6, 10
	s_sub_i32 s0, s2, s0
	s_cmp_lt_i32 s0, 0
	s_movk_i32 s29, 0x161
	s_cselect_b32 s5, s29, 0x160
	s_mul_i32 s0, s5, s0
	s_add_i32 s0, s0, s4
	s_mul_hi_i32 s4, s0, 0x2e8ba2e9
	s_lshr_b32 s5, s4, 31
	s_ashr_i32 s4, s4, 5
	s_add_i32 s4, s4, s5
	s_lshl_b32 s5, s4, 3
	s_mulk_i32 s4, 0xb0
	s_sub_i32 s4, s0, s4
	s_sext_i32_i16 s0, s4
	s_bfe_u32 s0, s0, 0x3001c
	s_add_i32 s7, s4, s0
	s_sext_i32_i16 s0, s7
	s_and_b32 s7, s7, 0xfff8
	s_sub_i32 s4, s4, s7
	s_sext_i32_i16 s4, s4
	v_lshrrev_b32_e32 v5, 2, v3
	v_lshlrev_b32_e32 v6, 1, v3
	v_and_b32_e32 v1, 0xc0, v1
	s_lshr_b32 s0, s0, 3
	s_add_i32 s18, s5, s4
	v_and_b32_e32 v5, 4, v5
	v_and_b32_e32 v6, 24, v6
	v_sub_u32_e32 v0, v0, v1
	s_ashr_i32 s19, s18, 31
	s_bfe_i64 s[10:11], s[0:1], 0x100000
	v_or3_b32 v4, v4, v5, v6
	v_lshlrev_b32_e32 v5, 5, v13
	v_ashrrev_i16_sdwa v0, v2, sext(v0) dst_sel:DWORD dst_unused:UNUSED_PAD src0_sel:DWORD src1_sel:BYTE_0
	s_lshl_b64 s[4:5], s[18:19], 19
	s_lshl_b64 s[10:11], s[10:11], 19
	v_and_b32_e32 v5, 32, v5
	v_bfe_i32 v14, v0, 0, 16
	s_add_u32 s22, s26, s10
	v_add_lshl_u32 v0, v5, v14, 1
	s_addc_u32 s23, s27, s11
	s_add_i32 s19, s28, 0
	v_lshl_add_u32 v132, v4, 11, v0
	s_add_i32 m0, s19, 0x10000
	v_lshl_add_u32 v134, v3, 11, v0
	global_load_lds_dwordx4 v132, s[22:23]
	s_add_i32 m0, s19, 0x12000
	s_add_u32 s10, s22, 0x40000
	global_load_lds_dwordx4 v128, s[22:23]
	s_addc_u32 s11, s23, 0
	s_add_i32 m0, s19, 0x14000
	v_mov_b32_e32 v133, 0
	global_load_lds_dwordx4 v132, s[10:11]
	s_add_i32 m0, s19, 0x16000
	s_add_u32 s20, s74, s4
	s_addc_u32 s21, s75, s5
	s_add_i32 s30, s19, 0x2000
	global_load_lds_dwordx4 v128, s[10:11]
	s_mov_b32 m0, s19
	s_add_u32 s4, s20, 0x40000
	global_load_lds_dwordx4 v134, s[20:21]
	s_mov_b32 m0, s30
	s_addc_u32 s5, s21, 0
	s_add_i32 s31, s19, 0x4000
	global_load_lds_dwordx4 v130, s[20:21]
	s_mov_b32 m0, s31
	s_add_i32 s33, s19, 0x6000
	global_load_lds_dwordx4 v134, s[4:5]
	s_mov_b32 m0, s33
	v_mov_b32_e32 v129, v133
	global_load_lds_dwordx4 v130, s[4:5]
	v_mov_b32_e32 v135, v133
	v_mov_b32_e32 v131, v133
	s_cmp_eq_u32 s8, 1
	s_mov_b32 s40, 0
	v_lshl_add_u64 v[6:7], s[22:23], 0, v[132:133]
	v_lshl_add_u64 v[4:5], s[22:23], 0, v[128:129]
	v_lshl_add_u64 v[0:1], s[20:21], 0, v[134:135]
	s_cselect_b64 s[4:5], -1, 0
	s_cmp_lg_u32 s8, 1
	v_lshl_add_u64 v[2:3], s[20:21], 0, v[130:131]
	s_cbranch_scc1 .LBB0_699
	s_barrier

.LBB0_862:
	s_or_b64 exec, exec, s[0:1]
	s_waitcnt lgkmcnt(0)
	v_mov_b32_e32 v0, v181
	s_barrier
	s_cmp_eq_u32 s66, 0x100
	s_cbranch_scc0 .Lrs_orig_i1
	v_lshrrev_b32_e32 v4, 8, v181
	v_and_b32_e32 v5, 0xff, v181
	v_mov_b32_e32 v9, 0x358637bd
	v_readfirstlane_b32 s4, v4
	v_lshlrev_b32_e32 v6, 6, v5
	v_lshlrev_b32_e32 v7, 2, v5
	s_nop 3
	s_and_b32 s5, s2, 7
	s_lshr_b32 s9, s2, 3
	s_lshl_b32 s5, s5, 4
	s_and_b32 s10, s9, 7
	s_add_i32 s5, s5, s10
	s_lshl_b32 s10, s4, 10
	s_add_i32 s10, s10, 0x20000
	v_add_u32_e32 v7, s10, v7
	s_lshl_b32 s11, s5, 14
	s_add_u32 s12, s68, s11
	s_addc_u32 s13, s69, 0
	s_add_u32 s98, s12, 0x20000
	s_addc_u32 s99, s13, 0
	global_load_dwordx4 v[16:19], v6, s[12:13] offset:0
	global_load_dwordx4 v[20:23], v6, s[12:13] offset:16
	global_load_dwordx4 v[24:27], v6, s[12:13] offset:32
	global_load_dwordx4 v[28:31], v6, s[12:13] offset:48
	global_load_dwordx4 v[32:35], v6, s[98:99] offset:0
	global_load_dwordx4 v[36:39], v6, s[98:99] offset:16
	global_load_dwordx4 v[40:43], v6, s[98:99] offset:32
	global_load_dwordx4 v[44:47], v6, s[98:99] offset:48
	s_waitcnt vmcnt(4)
	v_add_f32_e32 v12, v16, v17
	v_add_f32_e32 v48, v18, v19
	v_add_f32_e32 v12, v12, v48
	v_add_f32_e32 v13, v20, v21
	v_add_f32_e32 v48, v22, v23
	v_add_f32_e32 v13, v13, v48
	v_add_f32_e32 v14, v24, v25
	v_add_f32_e32 v48, v26, v27
	v_add_f32_e32 v14, v14, v48
	v_add_f32_e32 v15, v28, v29
	v_add_f32_e32 v48, v30, v31
	v_add_f32_e32 v15, v15, v48
	v_add_f32_e32 v12, v12, v13
	v_add_f32_e32 v12, v12, v14
	v_add_f32_e32 v12, v12, v15
	v_fmamk_f32 v12, v12, 0x3a800000, v9
	v_rsq_f32_e32 v10, v12
	s_waitcnt vmcnt(0)
	v_add_f32_e32 v12, v32, v33
	v_add_f32_e32 v48, v34, v35
	v_add_f32_e32 v12, v12, v48
	v_add_f32_e32 v13, v36, v37
	v_add_f32_e32 v48, v38, v39
	v_add_f32_e32 v13, v13, v48
	v_add_f32_e32 v14, v40, v41
	v_add_f32_e32 v48, v42, v43
	v_add_f32_e32 v14, v14, v48
	v_add_f32_e32 v15, v44, v45
	v_add_f32_e32 v48, v46, v47
	v_add_f32_e32 v15, v15, v48
	v_add_f32_e32 v12, v12, v13
	v_add_f32_e32 v12, v12, v14
	v_add_f32_e32 v12, v12, v15
	v_fmamk_f32 v12, v12, 0x3a800000, v9
	v_rsq_f32_e32 v11, v12
	s_lshl_b32 s11, s4, 5
	s_add_i32 s11, s11, s9
	s_add_i32 s10, s11, 0
	s_cmp_ge_u32 s10, 80
	s_cselect_b64 vcc, -1, 0
	v_cndmask_b32_e32 v12, v10, v11, vcc
	ds_write_b32 v7, v12 offset:0
	s_add_i32 s10, s11, 64
	s_cmp_ge_u32 s10, 80
	s_cselect_b64 vcc, -1, 0
	v_cndmask_b32_e32 v12, v10, v11, vcc
	ds_write_b32 v7, v12 offset:2048
	s_cmp_eq_u32 s4, 0
	s_cbranch_scc0 .Lrs_join_i1
	s_add_i32 s10, s11, 128
	s_cmp_ge_u32 s10, 80
	s_cselect_b64 vcc, -1, 0
	v_cndmask_b32_e32 v12, v10, v11, vcc
	ds_write_b32 v7, v12 offset:4096
	s_branch .Lrs_join_i1
.Lrs_orig_i1:
	s_mov_b64 s[4:5], 0x500
	v_and_b32_e32 v2, 0xff, v0
	v_ashrrev_i32_e32 v4, 8, v0
	v_lshlrev_b32_e32 v0, 2, v2
	v_lshl_or_b32 v0, v4, 10, v0
	v_add_u32_e32 v0, 0, v0
	v_add_u32_e32 v3, 0x20000, v0
	v_mov_b64_e32 v[0:1], s[2:3]
	v_mad_i64_i32 v[0:1], s[0:1], s72, v4, v[0:1]
	s_mov_b64 s[0:1], 0
	s_mov_b32 s10, 0x66666667
	s_movk_i32 s11, 0x50
	v_mov_b32_e32 v4, 0x358637bd
	v_mov_b32_e32 v5, 0xa0
	v_mov_b32_e32 v6, 0xa1
	s_branch .LBB0_864

.Lrs_join_i1:
	v_mov_b32_e32 v8, v181
	s_cmpk_lt_i32 s2, 0x500
	s_waitcnt lgkmcnt(0)
	s_barrier
	s_cselect_b64 s[0:1], -1, 0
	s_cmpk_gt_i32 s2, 0x4ff
	v_readfirstlane_b32 s4, v8
	s_cbranch_scc1 .LBB0_868
	s_lshr_b32 s5, s3, 29
	s_add_i32 s5, s2, s5
	s_ashr_i32 s6, s5, 3
	s_and_b32 s5, s5, -8
	s_sub_i32 s5, s2, s5
	s_cmp_lt_i32 s5, 0
	s_movk_i32 s7, 0xa1
	s_cselect_b32 s7, s7, 0xa0
	s_mul_i32 s5, s7, s5
	s_add_i32 s5, s5, s6
	s_mul_hi_i32 s6, s5, 0x66666667
	s_lshr_b32 s7, s6, 31
	s_ashr_i32 s6, s6, 5
	s_add_i32 s6, s6, s7
	s_lshl_b32 s7, s6, 3
	s_mulk_i32 s6, 0x50
	s_sub_i32 s5, s5, s6
	s_bfe_i32 s6, s5, 0x80000
	s_bfe_u32 s6, s6, 0x3000c
	s_add_i32 s6, s5, s6
	s_bfe_i32 s8, s6, 0x80000
	s_and_b32 s6, s6, 0xf8
	s_sub_i32 s5, s5, s6
	s_sext_i32_i16 s9, s8
	s_sext_i32_i8 s5, s5
	s_add_i32 s8, s7, s5
	s_ashr_i32 s10, s9, 3

.Lrs_join_g1:
	v_readlane_b32 s0, v246, 58
	v_mov_b32_e32 v9, v181
	v_readlane_b32 s1, v246, 59
	s_waitcnt lgkmcnt(0)
	s_barrier
	s_andn2_b64 vcc, exec, s[0:1]
	v_readfirstlane_b32 s1, v9
	s_cbranch_vccnz .LBB0_1386
	v_lshlrev_b32_e32 v0, 4, v9
	v_add_u32_e32 v1, 0x2000, v0
	v_ashrrev_i32_e32 v2, 31, v1
	v_lshrrev_b32_e32 v2, 22, v2
	v_add_u32_e32 v2, v1, v2
	v_ashrrev_i32_e32 v8, 10, v2
	v_mul_i32_i24_e32 v2, 0x400, v8
	v_sub_u32_e32 v1, v1, v2
	v_lshrrev_b32_e32 v2, 4, v1
	v_bitop3_b32 v1, v2, v1, 32 bitop3:0x6c
	v_ashrrev_i32_e32 v2, 31, v1
	v_lshrrev_b32_e32 v2, 26, v2
	v_add_u32_e32 v2, v1, v2
	v_lshlrev_b32_e32 v3, 3, v8
	v_ashrrev_i32_e32 v10, 6, v2
	v_and_b32_e32 v3, -16, v3
	v_add_u32_e32 v3, v10, v3
	v_and_b32_e32 v4, 3, v10
	s_mov_b32 s0, 0x1fffe0
	v_lshrrev_b32_e32 v5, 2, v3
	v_lshlrev_b32_e32 v6, 1, v3
	v_and_b32_e32 v2, 0xc0, v2
	v_and_or_b32 v4, v3, s0, v4
	v_and_b32_e32 v5, 4, v5
	v_and_b32_e32 v6, 24, v6
	v_sub_u32_e32 v1, v1, v2
	v_mov_b32_e32 v2, 1
	v_or3_b32 v4, v4, v5, v6
	v_lshlrev_b32_e32 v5, 5, v8
	v_ashrrev_i16_sdwa v1, v2, sext(v1) dst_sel:DWORD dst_unused:UNUSED_PAD src0_sel:DWORD src1_sel:BYTE_0
	v_and_b32_e32 v5, 32, v5
	v_bfe_i32 v11, v1, 0, 16
	v_add_lshl_u32 v1, v5, v11, 1
	s_waitcnt vmcnt(6)
	v_lshl_add_u32 v128, v4, 11, v1
	v_lshl_add_u32 v130, v3, 11, v1
	v_bfe_i32 v1, v9, 27, 1
	v_lshrrev_b32_e32 v1, 22, v1
	v_add_u32_e32 v1, v0, v1
	v_and_b32_e32 v1, 0xfffffc00, v1
	v_sub_u32_e32 v0, v0, v1
	v_lshrrev_b32_e32 v1, 4, v0
	v_ashrrev_i32_e32 v3, 31, v9
	v_bitop3_b32 v0, v1, v0, 32 bitop3:0x6c
	v_lshrrev_b32_e32 v3, 26, v3
	v_ashrrev_i32_e32 v1, 31, v0
	v_add_u32_e32 v3, v9, v3
	v_lshrrev_b32_e32 v1, 26, v1
	v_ashrrev_i32_e32 v13, 6, v3
	v_add_u32_e32 v1, v0, v1
	v_lshlrev_b32_e32 v3, 3, v13
	v_ashrrev_i32_e32 v12, 6, v1
	v_and_b32_e32 v3, -16, v3
	s_add_u32 s26, s64, 0x1480000
	v_add_u32_e32 v3, v12, v3
	v_and_b32_e32 v4, 3, v12
	s_addc_u32 s27, s65, 0
	v_and_or_b32 v4, v3, s0, v4
	s_lshr_b32 s0, s3, 29
	s_add_i32 s0, s2, s0
	s_ashr_i32 s6, s1, 6
	s_ashr_i32 s4, s0, 3
	s_and_b32 s0, s0, -8
	s_ashr_i32 s8, s1, 8
	s_lshl_b32 s28, s6, 10
	s_sub_i32 s0, s2, s0
	s_cmp_lt_i32 s0, 0
	s_movk_i32 s29, 0x161
	s_cselect_b32 s5, s29, 0x160
	s_mul_i32 s0, s5, s0
	s_add_i32 s0, s0, s4
	s_mul_hi_i32 s4, s0, 0x2e8ba2e9
	s_lshr_b32 s5, s4, 31
	s_ashr_i32 s4, s4, 5
	s_add_i32 s4, s4, s5
	s_lshl_b32 s5, s4, 3
	s_mulk_i32 s4, 0xb0
	s_sub_i32 s4, s0, s4
	s_sext_i32_i16 s0, s4
	s_bfe_u32 s0, s0, 0x3001c
	s_add_i32 s7, s4, s0
	s_sext_i32_i16 s0, s7
	s_and_b32 s7, s7, 0xfff8
	s_sub_i32 s4, s4, s7
	s_sext_i32_i16 s4, s4
	v_lshrrev_b32_e32 v5, 2, v3
	v_lshlrev_b32_e32 v6, 1, v3
	v_and_b32_e32 v1, 0xc0, v1
	s_lshr_b32 s0, s0, 3
	s_add_i32 s18, s5, s4
	v_and_b32_e32 v5, 4, v5
	v_and_b32_e32 v6, 24, v6
	v_sub_u32_e32 v0, v0, v1
	s_ashr_i32 s19, s18, 31
	s_bfe_i64 s[10:11], s[0:1], 0x100000
	v_or3_b32 v4, v4, v5, v6
	v_lshlrev_b32_e32 v5, 5, v13
	v_ashrrev_i16_sdwa v0, v2, sext(v0) dst_sel:DWORD dst_unused:UNUSED_PAD src0_sel:DWORD src1_sel:BYTE_0
	s_lshl_b64 s[4:5], s[18:19], 19
	s_lshl_b64 s[10:11], s[10:11], 19
	v_and_b32_e32 v5, 32, v5
	v_bfe_i32 v14, v0, 0, 16
	s_add_u32 s22, s26, s10
	v_add_lshl_u32 v0, v5, v14, 1
	s_addc_u32 s23, s27, s11
	s_add_i32 s19, s28, 0
	s_waitcnt vmcnt(4)
	v_lshl_add_u32 v132, v4, 11, v0
	s_add_i32 m0, s19, 0x10000
	v_lshl_add_u32 v134, v3, 11, v0
	global_load_lds_dwordx4 v132, s[22:23]
	s_add_i32 m0, s19, 0x12000
	s_add_u32 s10, s22, 0x40000
	global_load_lds_dwordx4 v128, s[22:23]
	s_addc_u32 s11, s23, 0
	s_add_i32 m0, s19, 0x14000
	v_mov_b32_e32 v133, 0
	global_load_lds_dwordx4 v132, s[10:11]
	s_add_i32 m0, s19, 0x16000
	s_add_u32 s20, s74, s4
	s_addc_u32 s21, s75, s5
	s_add_i32 s30, s19, 0x2000
	global_load_lds_dwordx4 v128, s[10:11]
	s_mov_b32 m0, s19
	s_add_u32 s4, s20, 0x40000
	global_load_lds_dwordx4 v134, s[20:21]
	s_mov_b32 m0, s30
	s_addc_u32 s5, s21, 0
	s_add_i32 s31, s19, 0x4000
	global_load_lds_dwordx4 v130, s[20:21]
	s_mov_b32 m0, s31
	s_add_i32 s33, s19, 0x6000
	global_load_lds_dwordx4 v134, s[4:5]
	s_mov_b32 m0, s33
	v_mov_b32_e32 v129, v133
	global_load_lds_dwordx4 v130, s[4:5]
	v_mov_b32_e32 v135, v133
	v_mov_b32_e32 v131, v133
	s_cmp_eq_u32 s8, 1
	s_mov_b32 s40, 0
	v_lshl_add_u64 v[6:7], s[22:23], 0, v[132:133]
	v_lshl_add_u64 v[4:5], s[22:23], 0, v[128:129]
	v_lshl_add_u64 v[0:1], s[20:21], 0, v[134:135]
	s_cselect_b64 s[4:5], -1, 0
	s_cmp_lg_u32 s8, 1
	v_lshl_add_u64 v[2:3], s[20:21], 0, v[130:131]
	s_cbranch_scc1 .LBB0_1373
	s_barrier
